# nt_on_kv_cache_f32_output_stores
# speedup vs baseline: 1.0008x; 1.0008x over previous
.LBB0_267:
	s_andn2_b64 vcc, exec, s[4:5]
	s_cbranch_vccnz .LBB0_205
	s_lshr_b32 s14, s58, 2
	s_and_b32 s4, s17, 0x300
	v_or_b32_e32 v141, s4, v138
	s_mul_i32 s4, s14, 0x1400000
	s_mul_hi_u32 s5, s14, 0x1400000
	s_add_u32 s4, s31, s4
	s_addc_u32 s5, s35, s5
	v_lshlrev_b32_e32 v196, 1, v141
	v_lshl_add_u64 v[142:143], s[4:5], 0, v[196:197]
	s_cmp_eq_u32 s14, 1
	s_mov_b32 s4, 0x5000000
	s_cselect_b32 s4, s4, 0xd000000
	s_add_u32 s4, s56, s4
	s_addc_u32 s5, s57, 0
	v_lshlrev_b32_e32 v196, 2, v141
	s_cmp_gt_u32 s58, 3
	v_lshl_add_u64 v[144:145], s[4:5], 0, v[196:197]
	s_cselect_b64 s[4:5], -1, 0
	s_cmp_lt_i32 s8, 32
	s_cselect_b64 s[14:15], -1, 0
	s_and_b64 s[14:15], s[4:5], s[14:15]
	s_ashr_i32 s4, s16, 8
	s_ashr_i32 s5, s4, 31
	v_ashrrev_i32_e32 v141, 31, v140
	s_lshl_b64 s[4:5], s[4:5], 22
	v_lshlrev_b64 v[148:149], 11, v[140:141]
	v_lshlrev_b32_e32 v141, 12, v140
	v_lshl_add_u64 v[146:147], v[144:145], 0, s[4:5]
	v_and_b32_e32 v196, 0xcf000, v141
	v_cndmask_b32_e64 v141, 0, 1, s[14:15]
	v_lshl_add_u64 v[148:149], v[142:143], 0, v[148:149]
	v_lshl_add_u64 v[150:151], v[146:147], 0, v[196:197]
	v_cmp_ne_u32_e64 s[4:5], 1, v141
	s_andn2_b64 vcc, exec, s[14:15]
	v_cvt_pk_bf16_f32 v154, v126, v127
	v_cvt_pk_bf16_f32 v155, v128, v129
	v_cvt_pk_bf16_f32 v156, v122, v123
	v_cvt_pk_bf16_f32 v157, v124, v125
	global_store_dwordx4 v[148:149], v[154:157], off
	s_cbranch_vccnz .LBB0_270
	global_store_dwordx4 v[150:151], v[126:129], off nt
	global_store_dwordx4 v[150:151], v[122:125], off offset:16 nt
.LBB0_270:
	s_and_b64 vcc, exec, s[4:5]
	s_nop 0
	v_cvt_pk_bf16_f32 v122, v118, v119
	v_cvt_pk_bf16_f32 v123, v120, v121
	v_cvt_pk_bf16_f32 v124, v114, v115
	v_cvt_pk_bf16_f32 v125, v116, v117
	global_store_dwordx4 v[148:149], v[122:125], off offset:256
	s_cbranch_vccnz .LBB0_272
	global_store_dwordx4 v[150:151], v[118:121], off offset:512 nt
	global_store_dwordx4 v[150:151], v[114:117], off offset:528 nt
.LBB0_272:
	s_nop 1
	v_or_b32_e32 v116, 16, v140
	v_ashrrev_i32_e32 v117, 31, v116
	v_lshlrev_b64 v[114:115], 11, v[116:117]
	v_lshlrev_b32_e32 v116, 12, v116
	v_and_b32_e32 v196, 0xdf000, v116
	v_lshl_add_u64 v[114:115], v[142:143], 0, v[114:115]
	v_lshl_add_u64 v[116:117], v[146:147], 0, v[196:197]
	s_and_b64 vcc, exec, s[4:5]
	v_cvt_pk_bf16_f32 v118, v110, v111
	v_cvt_pk_bf16_f32 v119, v112, v113
	v_cvt_pk_bf16_f32 v120, v106, v107
	v_cvt_pk_bf16_f32 v121, v108, v109
	global_store_dwordx4 v[114:115], v[118:121], off
	s_cbranch_vccnz .LBB0_274
	global_store_dwordx4 v[116:117], v[110:113], off nt
	global_store_dwordx4 v[116:117], v[106:109], off offset:16 nt
.LBB0_274:
	s_and_b64 vcc, exec, s[4:5]
	s_nop 0
	v_cvt_pk_bf16_f32 v106, v102, v103
	v_cvt_pk_bf16_f32 v107, v104, v105
	v_cvt_pk_bf16_f32 v108, v98, v99
	v_cvt_pk_bf16_f32 v109, v100, v101
	global_store_dwordx4 v[114:115], v[106:109], off offset:256
	s_cbranch_vccnz .LBB0_276
	global_store_dwordx4 v[116:117], v[102:105], off offset:512 nt
	global_store_dwordx4 v[116:117], v[98:101], off offset:528 nt
.LBB0_276:
	s_nop 1
	v_or_b32_e32 v100, 32, v140
	v_ashrrev_i32_e32 v101, 31, v100
	v_lshlrev_b64 v[98:99], 11, v[100:101]
	v_lshlrev_b32_e32 v100, 12, v100
	v_and_b32_e32 v196, 0xef000, v100
	v_lshl_add_u64 v[98:99], v[142:143], 0, v[98:99]
	v_lshl_add_u64 v[100:101], v[146:147], 0, v[196:197]
	s_and_b64 vcc, exec, s[4:5]
	v_cvt_pk_bf16_f32 v102, v94, v95
	v_cvt_pk_bf16_f32 v103, v96, v97
	v_cvt_pk_bf16_f32 v104, v90, v91
	v_cvt_pk_bf16_f32 v105, v92, v93
	global_store_dwordx4 v[98:99], v[102:105], off
	s_cbranch_vccnz .LBB0_278
	global_store_dwordx4 v[100:101], v[94:97], off nt
	global_store_dwordx4 v[100:101], v[90:93], off offset:16 nt
.LBB0_278:
	s_and_b64 vcc, exec, s[4:5]
	s_nop 0
	v_cvt_pk_bf16_f32 v90, v86, v87
	v_cvt_pk_bf16_f32 v91, v88, v89
	v_cvt_pk_bf16_f32 v92, v82, v83
	v_cvt_pk_bf16_f32 v93, v84, v85
	global_store_dwordx4 v[98:99], v[90:93], off offset:256
	s_cbranch_vccnz .LBB0_280
	global_store_dwordx4 v[100:101], v[86:89], off offset:512 nt
	global_store_dwordx4 v[100:101], v[82:85], off offset:528 nt
.LBB0_280:
	s_nop 1
	v_or_b32_e32 v84, 48, v140
	v_ashrrev_i32_e32 v85, 31, v84
	v_lshlrev_b64 v[82:83], 11, v[84:85]
	v_lshlrev_b32_e32 v84, 12, v84
	v_and_b32_e32 v196, 0xff000, v84
	v_lshl_add_u64 v[82:83], v[142:143], 0, v[82:83]
	v_lshl_add_u64 v[84:85], v[146:147], 0, v[196:197]
	s_and_b64 vcc, exec, s[4:5]
	v_cvt_pk_bf16_f32 v86, v78, v79
	v_cvt_pk_bf16_f32 v87, v80, v81
	v_cvt_pk_bf16_f32 v88, v74, v75
	v_cvt_pk_bf16_f32 v89, v76, v77
	global_store_dwordx4 v[82:83], v[86:89], off
	s_cbranch_vccnz .LBB0_282
	global_store_dwordx4 v[84:85], v[78:81], off nt
	global_store_dwordx4 v[84:85], v[74:77], off offset:16 nt
.LBB0_282:
	s_and_b64 vcc, exec, s[4:5]
	s_nop 0
	v_cvt_pk_bf16_f32 v74, v70, v71
	v_cvt_pk_bf16_f32 v75, v72, v73
	v_cvt_pk_bf16_f32 v76, v66, v67
	v_cvt_pk_bf16_f32 v77, v68, v69
	global_store_dwordx4 v[82:83], v[74:77], off offset:256
	s_cbranch_vccnz .LBB0_284
	global_store_dwordx4 v[84:85], v[70:73], off offset:512 nt
	global_store_dwordx4 v[84:85], v[66:69], off offset:528 nt
.LBB0_284:
	s_nop 0
	v_add_u32_e32 v70, 0x80, v140
	v_ashrrev_i32_e32 v66, 8, v70
	v_ashrrev_i32_e32 v67, 31, v66
	v_ashrrev_i32_e32 v71, 31, v70
	v_lshlrev_b64 v[66:67], 22, v[66:67]
	v_lshlrev_b64 v[68:69], 11, v[70:71]
	v_lshlrev_b32_e32 v70, 12, v70
	v_lshl_add_u64 v[66:67], v[144:145], 0, v[66:67]
	v_and_b32_e32 v196, 0xcf000, v70
	v_lshl_add_u64 v[68:69], v[142:143], 0, v[68:69]
	v_lshl_add_u64 v[70:71], v[66:67], 0, v[196:197]
	s_and_b64 vcc, exec, s[4:5]
	v_cvt_pk_bf16_f32 v72, v62, v63
	v_cvt_pk_bf16_f32 v73, v64, v65
	v_cvt_pk_bf16_f32 v74, v58, v59
	v_cvt_pk_bf16_f32 v75, v60, v61
	global_store_dwordx4 v[68:69], v[72:75], off
	s_cbranch_vccnz .LBB0_286
	global_store_dwordx4 v[70:71], v[62:65], off nt
	global_store_dwordx4 v[70:71], v[58:61], off offset:16 nt
.LBB0_286:
	s_and_b64 vcc, exec, s[4:5]
	s_nop 0
	v_cvt_pk_bf16_f32 v58, v54, v55
	v_cvt_pk_bf16_f32 v59, v56, v57
	v_cvt_pk_bf16_f32 v60, v50, v51
	v_cvt_pk_bf16_f32 v61, v52, v53
	global_store_dwordx4 v[68:69], v[58:61], off offset:256
	s_cbranch_vccnz .LBB0_288
	global_store_dwordx4 v[70:71], v[54:57], off offset:512 nt
	global_store_dwordx4 v[70:71], v[50:53], off offset:528 nt
.LBB0_288:
	s_nop 1
	v_add_u32_e32 v52, 0x90, v140
	v_ashrrev_i32_e32 v53, 31, v52
	v_lshlrev_b64 v[50:51], 11, v[52:53]
	v_lshlrev_b32_e32 v52, 12, v52
	v_and_b32_e32 v196, 0xdf000, v52
	v_lshl_add_u64 v[50:51], v[142:143], 0, v[50:51]
	v_lshl_add_u64 v[52:53], v[66:67], 0, v[196:197]
	s_and_b64 vcc, exec, s[4:5]
	v_cvt_pk_bf16_f32 v54, v46, v47
	v_cvt_pk_bf16_f32 v55, v48, v49
	v_cvt_pk_bf16_f32 v56, v42, v43
	v_cvt_pk_bf16_f32 v57, v44, v45
	global_store_dwordx4 v[50:51], v[54:57], off
	s_cbranch_vccnz .LBB0_290
	global_store_dwordx4 v[52:53], v[46:49], off nt
	global_store_dwordx4 v[52:53], v[42:45], off offset:16 nt
.LBB0_290:
	s_and_b64 vcc, exec, s[4:5]
	s_nop 0
	v_cvt_pk_bf16_f32 v42, v38, v39
	v_cvt_pk_bf16_f32 v43, v40, v41
	v_cvt_pk_bf16_f32 v44, v34, v35
	v_cvt_pk_bf16_f32 v45, v36, v37
	global_store_dwordx4 v[50:51], v[42:45], off offset:256
	s_cbranch_vccnz .LBB0_292
	global_store_dwordx4 v[52:53], v[38:41], off offset:512 nt
	global_store_dwordx4 v[52:53], v[34:37], off offset:528 nt
.LBB0_292:
	s_nop 1
	v_add_u32_e32 v36, 0xa0, v140
	v_ashrrev_i32_e32 v37, 31, v36
	v_lshlrev_b64 v[34:35], 11, v[36:37]
	v_lshlrev_b32_e32 v36, 12, v36
	v_and_b32_e32 v196, 0xef000, v36
	v_lshl_add_u64 v[34:35], v[142:143], 0, v[34:35]
	v_lshl_add_u64 v[36:37], v[66:67], 0, v[196:197]
	s_and_b64 vcc, exec, s[4:5]
	v_cvt_pk_bf16_f32 v38, v30, v31
	v_cvt_pk_bf16_f32 v39, v32, v33
	v_cvt_pk_bf16_f32 v40, v26, v27
	v_cvt_pk_bf16_f32 v41, v28, v29
	global_store_dwordx4 v[34:35], v[38:41], off
	s_cbranch_vccnz .LBB0_294
	global_store_dwordx4 v[36:37], v[30:33], off nt
	global_store_dwordx4 v[36:37], v[26:29], off offset:16 nt
.LBB0_294:
	s_and_b64 vcc, exec, s[4:5]
	s_nop 0
	v_cvt_pk_bf16_f32 v26, v22, v23
	v_cvt_pk_bf16_f32 v27, v24, v25
	v_cvt_pk_bf16_f32 v28, v18, v19
	v_cvt_pk_bf16_f32 v29, v20, v21
	global_store_dwordx4 v[34:35], v[26:29], off offset:256
	s_cbranch_vccnz .LBB0_296
	global_store_dwordx4 v[36:37], v[22:25], off offset:512 nt
	global_store_dwordx4 v[36:37], v[18:21], off offset:528 nt
.LBB0_296:
	s_nop 1
	v_add_u32_e32 v20, 0xb0, v140
	v_ashrrev_i32_e32 v21, 31, v20
	v_lshlrev_b64 v[18:19], 11, v[20:21]
	v_lshlrev_b32_e32 v20, 12, v20
	v_and_b32_e32 v196, 0xff000, v20
	v_lshl_add_u64 v[18:19], v[142:143], 0, v[18:19]
	v_lshl_add_u64 v[20:21], v[66:67], 0, v[196:197]
	s_and_b64 vcc, exec, s[4:5]
	v_cvt_pk_bf16_f32 v22, v14, v15
	v_cvt_pk_bf16_f32 v23, v16, v17
	v_cvt_pk_bf16_f32 v24, v10, v11
	v_cvt_pk_bf16_f32 v25, v12, v13
	global_store_dwordx4 v[18:19], v[22:25], off
	s_cbranch_vccnz .LBB0_298
	global_store_dwordx4 v[20:21], v[14:17], off nt
	global_store_dwordx4 v[20:21], v[10:13], off offset:16 nt
.LBB0_298:
	s_and_b64 vcc, exec, s[4:5]
	s_nop 0
	v_cvt_pk_bf16_f32 v10, v6, v7
	v_cvt_pk_bf16_f32 v11, v8, v9
	v_cvt_pk_bf16_f32 v12, v2, v3
	v_cvt_pk_bf16_f32 v13, v4, v5
	global_store_dwordx4 v[18:19], v[10:13], off offset:256
	s_cbranch_vccnz .LBB0_205
	global_store_dwordx4 v[20:21], v[6:9], off offset:512 nt
	global_store_dwordx4 v[20:21], v[2:5], off offset:528 nt
	s_branch .LBB0_205
